# fa (sample instance) epilogue: 32 dwordx2 stores paired into 16 dwordx4 with v_permlane16_swap, cvts retargeted into free quads; placement preserved
# speedup vs baseline: 1.0035x; 1.0035x over previous
.LBB0_73:
	s_ashr_i32 s31, s30, 31
	s_lshl_b64 s[14:15], s[30:31], 17
	v_readlane_b32 s40, v254, 29
	v_mov_b64_e32 v[0:1], 0x400
	v_readlane_b32 s41, v254, 30
	s_add_u32 s40, s40, s14
	v_cmp_lt_i64_e32 vcc, s[8:9], v[0:1]
	s_addc_u32 s41, s41, s15
	s_and_b64 s[14:15], vcc, exec
	s_cselect_b32 s45, s41, s35
	s_cselect_b32 s44, s40, s34
	s_ashr_i32 s13, s12, 31
	s_lshl_b64 s[14:15], s[12:13], 17
	s_add_u32 s42, s96, s14
	s_addc_u32 s43, s97, s15
	s_and_b64 s[14:15], vcc, exec
	s_cselect_b32 s15, s43, s19
	s_cselect_b32 s14, s42, s18
	s_add_i32 vcc_hi, 16, 0x10000
	v_add_u32_e32 v107, vcc_hi, v101
	ds_read_b128 v[0:3], v107
	ds_read_b128 v[4:7], v107 offset:1024
	ds_read_b128 v[8:11], v107 offset:2048
	ds_read_b128 v[12:15], v107 offset:3072
	v_mov_b64_e32 v[250:251], 0x300
	v_mov_b64_e32 v[248:249], 0x2ff
	s_add_u32 s48, s34, 0x10080
	s_addc_u32 s49, s35, 0
	s_add_i32 s16, s20, 0xc000
	v_lshl_add_u64 v[48:49], s[48:49], 0, v[98:99]
	s_mov_b32 m0, s16
	s_add_i32 s13, s20, 0xe000
	ds_read_b128 v[16:19], v106
	ds_read_b128 v[20:23], v106 offset:1024
	ds_read_b128 v[24:27], v106 offset:2048
	ds_read_b128 v[28:31], v106 offset:3072
	ds_read_b128 v[32:35], v106 offset:4096
	ds_read_b128 v[36:39], v106 offset:5120
	ds_read_b128 v[40:43], v106 offset:6144
	ds_read_b128 v[44:47], v106 offset:7168
	global_load_lds_dwordx4 v[48:49], off
	v_lshl_add_u64 v[48:49], s[48:49], 0, v[96:97]
	s_mov_b32 m0, s13
	s_nop 0
	global_load_lds_dwordx4 v[48:49], off
	s_waitcnt lgkmcnt(8)
	s_barrier
	s_waitcnt lgkmcnt(0)
	s_setprio 1
	s_waitcnt lgkmcnt(0)
	v_mfma_f32_16x16x32_bf16 v[48:51], v[0:3], v[16:19], 0
	v_mfma_f32_16x16x32_bf16 v[52:55], v[8:11], v[16:19], 0
	v_mfma_f32_16x16x32_bf16 v[56:59], v[0:3], v[24:27], 0
	v_mfma_f32_16x16x32_bf16 v[60:63], v[8:11], v[24:27], 0
	v_mfma_f32_16x16x32_bf16 v[64:67], v[0:3], v[32:35], 0
	v_mfma_f32_16x16x32_bf16 v[68:71], v[8:11], v[32:35], 0
	v_mfma_f32_16x16x32_bf16 v[72:75], v[0:3], v[40:43], 0
	v_mfma_f32_16x16x32_bf16 v[76:79], v[8:11], v[40:43], 0
	v_mfma_f32_16x16x32_bf16 v[48:51], v[4:7], v[20:23], v[48:51]
	v_mfma_f32_16x16x32_bf16 v[52:55], v[12:15], v[20:23], v[52:55]
	v_mfma_f32_16x16x32_bf16 v[56:59], v[4:7], v[28:31], v[56:59]
	v_mfma_f32_16x16x32_bf16 v[60:63], v[12:15], v[28:31], v[60:63]
	v_mfma_f32_16x16x32_bf16 v[64:67], v[4:7], v[36:39], v[64:67]
	v_mfma_f32_16x16x32_bf16 v[68:71], v[12:15], v[36:39], v[68:71]
	v_mfma_f32_16x16x32_bf16 v[72:75], v[4:7], v[44:47], v[72:75]
	v_mfma_f32_16x16x32_bf16 v[76:79], v[12:15], v[44:47], v[76:79]
	s_setprio 0
	s_barrier
	s_add_i32 vcc_lo, 16, 0x14000
	v_lshl_add_u64 v[138:139], s[18:19], 0, v[98:99]
	s_mov_b64 s[48:49], 0x100
	s_add_i32 vcc_hi, vcc_hi, s5
	v_add_u32_e32 v128, vcc_lo, v101
	v_lshl_add_u64 v[108:109], v[138:139], 0, s[48:49]
	s_mov_b32 m0, vcc_hi
	v_lshl_add_u64 v[140:141], s[18:19], 0, v[96:97]
	s_add_i32 s31, vcc_hi, 0x2000
	ds_read_b128 v[80:83], v128
	ds_read_b128 v[84:87], v128 offset:1024
	ds_read_b128 v[88:91], v128 offset:2048
	ds_read_b128 v[92:95], v128 offset:3072
	global_load_lds_dwordx4 v[108:109], off
	v_lshl_add_u64 v[108:109], v[140:141], 0, s[48:49]
	s_mov_b32 m0, s31
	s_nop 0
	global_load_lds_dwordx4 v[108:109], off
	s_barrier
	s_waitcnt lgkmcnt(0)
	s_setprio 1
	s_waitcnt lgkmcnt(0)
	v_mfma_f32_16x16x32_bf16 v[108:111], v[80:83], v[16:19], 0
	v_mfma_f32_16x16x32_bf16 v[16:19], v[88:91], v[16:19], 0
	v_mfma_f32_16x16x32_bf16 v[108:111], v[84:87], v[20:23], v[108:111]
	v_mfma_f32_16x16x32_bf16 v[16:19], v[92:95], v[20:23], v[16:19]
	v_mfma_f32_16x16x32_bf16 v[20:23], v[80:83], v[24:27], 0
	v_mfma_f32_16x16x32_bf16 v[24:27], v[88:91], v[24:27], 0
	v_mfma_f32_16x16x32_bf16 v[20:23], v[84:87], v[28:31], v[20:23]
	v_mfma_f32_16x16x32_bf16 v[24:27], v[92:95], v[28:31], v[24:27]
	v_mfma_f32_16x16x32_bf16 v[28:31], v[80:83], v[32:35], 0
	v_mfma_f32_16x16x32_bf16 v[32:35], v[88:91], v[32:35], 0
	v_mfma_f32_16x16x32_bf16 v[28:31], v[84:87], v[36:39], v[28:31]
	v_mfma_f32_16x16x32_bf16 v[32:35], v[92:95], v[36:39], v[32:35]
	v_mfma_f32_16x16x32_bf16 v[36:39], v[80:83], v[40:43], 0
	v_mfma_f32_16x16x32_bf16 v[40:43], v[88:91], v[40:43], 0
	v_mfma_f32_16x16x32_bf16 v[36:39], v[84:87], v[44:47], v[36:39]
	v_mfma_f32_16x16x32_bf16 v[40:43], v[92:95], v[44:47], v[40:43]
	s_setprio 0
	v_lshl_add_u64 v[212:213], s[34:35], 0, v[98:99]
	s_mov_b32 m0, s20
	v_lshl_add_u64 v[148:149], v[212:213], 0, s[48:49]
	v_lshl_add_u64 v[214:215], s[34:35], 0, v[96:97]
	s_barrier
	ds_read_b128 v[44:47], v106 offset:16384
	ds_read_b128 v[112:115], v106 offset:17408
	ds_read_b128 v[116:119], v106 offset:18432
	ds_read_b128 v[120:123], v106 offset:19456
	ds_read_b128 v[124:127], v106 offset:20480
	ds_read_b128 v[130:133], v106 offset:21504
	ds_read_b128 v[134:137], v106 offset:22528
	ds_read_b128 v[144:147], v106 offset:23552
	global_load_lds_dwordx4 v[148:149], off
	v_lshl_add_u64 v[148:149], v[214:215], 0, s[48:49]
	s_mov_b32 m0, s17
	s_nop 0
	global_load_lds_dwordx4 v[148:149], off
	s_barrier
	s_waitcnt lgkmcnt(0)
	s_setprio 1
	s_waitcnt lgkmcnt(0)
	v_mfma_f32_16x16x32_bf16 v[148:151], v[0:3], v[44:47], 0
	v_mfma_f32_16x16x32_bf16 v[156:159], v[0:3], v[116:119], 0
	v_mfma_f32_16x16x32_bf16 v[164:167], v[0:3], v[124:127], 0
	v_mfma_f32_16x16x32_bf16 v[0:3], v[0:3], v[134:137], 0
	v_mfma_f32_16x16x32_bf16 v[148:151], v[4:7], v[112:115], v[148:151]
	v_mfma_f32_16x16x32_bf16 v[152:155], v[8:11], v[44:47], 0
	v_mfma_f32_16x16x32_bf16 v[156:159], v[4:7], v[120:123], v[156:159]
	v_mfma_f32_16x16x32_bf16 v[160:163], v[8:11], v[116:119], 0
	v_mfma_f32_16x16x32_bf16 v[164:167], v[4:7], v[130:133], v[164:167]
	v_mfma_f32_16x16x32_bf16 v[168:171], v[8:11], v[124:127], 0
	v_mfma_f32_16x16x32_bf16 v[0:3], v[4:7], v[144:147], v[0:3]
	v_mfma_f32_16x16x32_bf16 v[4:7], v[8:11], v[134:137], 0
	v_mfma_f32_16x16x32_bf16 v[152:155], v[12:15], v[112:115], v[152:155]
	v_mfma_f32_16x16x32_bf16 v[160:163], v[12:15], v[120:123], v[160:163]
	v_mfma_f32_16x16x32_bf16 v[168:171], v[12:15], v[130:133], v[168:171]
	v_mfma_f32_16x16x32_bf16 v[4:7], v[12:15], v[144:147], v[4:7]
	s_setprio 0
	s_barrier
	s_add_u32 s48, s18, 0x10100
	s_addc_u32 s49, s19, 0
	s_add_i32 vcc_lo, vcc_lo, s5
	v_lshl_add_u64 v[8:9], s[48:49], 0, v[98:99]
	s_mov_b32 m0, vcc_lo
	s_nop 0
	global_load_lds_dwordx4 v[8:9], off
	v_lshl_add_u64 v[8:9], s[48:49], 0, v[96:97]
	s_add_i32 s48, vcc_lo, 0x2000
	s_mov_b32 m0, s48
	s_nop 0
	global_load_lds_dwordx4 v[8:9], off
	s_waitcnt vmcnt(6)
	s_barrier
	s_setprio 1
	v_mfma_f32_16x16x32_bf16 v[8:11], v[80:83], v[44:47], 0
	v_mfma_f32_16x16x32_bf16 v[12:15], v[88:91], v[44:47], 0
	v_mfma_f32_16x16x32_bf16 v[8:11], v[84:87], v[112:115], v[8:11]
	v_mfma_f32_16x16x32_bf16 v[12:15], v[92:95], v[112:115], v[12:15]
	v_mfma_f32_16x16x32_bf16 v[44:47], v[80:83], v[116:119], 0
	v_mfma_f32_16x16x32_bf16 v[112:115], v[88:91], v[116:119], 0
	v_mfma_f32_16x16x32_bf16 v[116:119], v[80:83], v[124:127], 0
	v_mfma_f32_16x16x32_bf16 v[80:83], v[80:83], v[134:137], 0
	v_mfma_f32_16x16x32_bf16 v[44:47], v[84:87], v[120:123], v[44:47]
	v_mfma_f32_16x16x32_bf16 v[112:115], v[92:95], v[120:123], v[112:115]
	v_mfma_f32_16x16x32_bf16 v[116:119], v[84:87], v[130:133], v[116:119]
	v_mfma_f32_16x16x32_bf16 v[120:123], v[88:91], v[124:127], 0
	v_mfma_f32_16x16x32_bf16 v[80:83], v[84:87], v[144:147], v[80:83]
	v_mfma_f32_16x16x32_bf16 v[84:87], v[88:91], v[134:137], 0
	v_mfma_f32_16x16x32_bf16 v[120:123], v[92:95], v[130:133], v[120:123]
	v_mfma_f32_16x16x32_bf16 v[84:87], v[92:95], v[144:147], v[84:87]
	s_setprio 0
	s_add_i32 s49, 16, 0x18000
	v_add_u32_e32 v143, s49, v101
	s_barrier
	ds_read_b128 v[88:91], v143
	ds_read_b128 v[92:95], v143 offset:1024
	ds_read_b128 v[124:127], v143 offset:2048
	ds_read_b128 v[130:133], v143 offset:3072
	s_add_u32 s50, s34, 0x10100
	s_addc_u32 s51, s35, 0
	s_mov_b32 m0, s24
	v_lshl_add_u64 v[196:197], s[50:51], 0, v[98:99]
	ds_read_b128 v[134:137], v106 offset:32768
	ds_read_b128 v[144:147], v106 offset:33792
	ds_read_b128 v[172:175], v106 offset:34816
	ds_read_b128 v[176:179], v106 offset:35840
	ds_read_b128 v[180:183], v106 offset:36864
	ds_read_b128 v[184:187], v106 offset:37888
	ds_read_b128 v[188:191], v106 offset:38912
	ds_read_b128 v[192:195], v106 offset:39936
	global_load_lds_dwordx4 v[196:197], off
	v_lshl_add_u64 v[196:197], s[50:51], 0, v[96:97]
	s_mov_b32 m0, s25
	s_nop 0
	global_load_lds_dwordx4 v[196:197], off
	s_waitcnt lgkmcnt(8)
	s_barrier
	s_waitcnt lgkmcnt(0)
	s_setprio 1
	s_waitcnt lgkmcnt(0)
	v_mfma_f32_16x16x32_bf16 v[48:51], v[88:91], v[134:137], v[48:51]
	v_mfma_f32_16x16x32_bf16 v[52:55], v[124:127], v[134:137], v[52:55]
	v_mfma_f32_16x16x32_bf16 v[56:59], v[88:91], v[172:175], v[56:59]
	v_mfma_f32_16x16x32_bf16 v[60:63], v[124:127], v[172:175], v[60:63]
	v_mfma_f32_16x16x32_bf16 v[64:67], v[88:91], v[180:183], v[64:67]
	v_mfma_f32_16x16x32_bf16 v[68:71], v[124:127], v[180:183], v[68:71]
	v_mfma_f32_16x16x32_bf16 v[72:75], v[88:91], v[188:191], v[72:75]
	v_mfma_f32_16x16x32_bf16 v[76:79], v[124:127], v[188:191], v[76:79]
	v_mfma_f32_16x16x32_bf16 v[48:51], v[92:95], v[144:147], v[48:51]
	v_mfma_f32_16x16x32_bf16 v[52:55], v[130:133], v[144:147], v[52:55]
	v_mfma_f32_16x16x32_bf16 v[56:59], v[92:95], v[176:179], v[56:59]
	v_mfma_f32_16x16x32_bf16 v[60:63], v[130:133], v[176:179], v[60:63]
	v_mfma_f32_16x16x32_bf16 v[64:67], v[92:95], v[184:187], v[64:67]
	v_mfma_f32_16x16x32_bf16 v[68:71], v[130:133], v[184:187], v[68:71]
	v_mfma_f32_16x16x32_bf16 v[72:75], v[92:95], v[192:195], v[72:75]
	v_mfma_f32_16x16x32_bf16 v[76:79], v[130:133], v[192:195], v[76:79]
	s_setprio 0
	s_barrier
	s_add_i32 s51, 16, 0x1c000
	s_mov_b64 s[52:53], 0x180
	s_add_i32 s50, s49, s5
	v_add_u32_e32 v236, s51, v101
	v_lshl_add_u64 v[138:139], v[138:139], 0, s[52:53]
	s_mov_b32 m0, s50
	s_add_i32 s49, s50, 0x2000
	ds_read_b128 v[196:199], v236
	ds_read_b128 v[200:203], v236 offset:1024
	ds_read_b128 v[204:207], v236 offset:2048
	ds_read_b128 v[208:211], v236 offset:3072
	global_load_lds_dwordx4 v[138:139], off
	v_lshl_add_u64 v[138:139], v[140:141], 0, s[52:53]
	s_mov_b32 m0, s49
	s_nop 0
	global_load_lds_dwordx4 v[138:139], off
	s_barrier
	s_waitcnt lgkmcnt(0)
	s_setprio 1
	s_waitcnt lgkmcnt(0)
	v_mfma_f32_16x16x32_bf16 v[108:111], v[196:199], v[134:137], v[108:111]
	v_mfma_f32_16x16x32_bf16 v[16:19], v[204:207], v[134:137], v[16:19]
	v_mfma_f32_16x16x32_bf16 v[20:23], v[196:199], v[172:175], v[20:23]
	v_mfma_f32_16x16x32_bf16 v[24:27], v[204:207], v[172:175], v[24:27]
	v_mfma_f32_16x16x32_bf16 v[28:31], v[196:199], v[180:183], v[28:31]
	v_mfma_f32_16x16x32_bf16 v[32:35], v[204:207], v[180:183], v[32:35]
	v_mfma_f32_16x16x32_bf16 v[36:39], v[196:199], v[188:191], v[36:39]
	v_mfma_f32_16x16x32_bf16 v[40:43], v[204:207], v[188:191], v[40:43]
	v_mfma_f32_16x16x32_bf16 v[108:111], v[200:203], v[144:147], v[108:111]
	v_mfma_f32_16x16x32_bf16 v[16:19], v[208:211], v[144:147], v[16:19]
	v_mfma_f32_16x16x32_bf16 v[20:23], v[200:203], v[176:179], v[20:23]
	v_mfma_f32_16x16x32_bf16 v[24:27], v[208:211], v[176:179], v[24:27]
	v_mfma_f32_16x16x32_bf16 v[28:31], v[200:203], v[184:187], v[28:31]
	v_mfma_f32_16x16x32_bf16 v[32:35], v[208:211], v[184:187], v[32:35]
	v_mfma_f32_16x16x32_bf16 v[36:39], v[200:203], v[192:195], v[36:39]
	v_mfma_f32_16x16x32_bf16 v[40:43], v[208:211], v[192:195], v[40:43]
	s_setprio 0
	s_mov_b32 m0, s36
	v_lshl_add_u64 v[138:139], v[212:213], 0, s[52:53]
	s_barrier
	ds_read_b128 v[134:137], v106 offset:49152
	ds_read_b128 v[144:147], v106 offset:50176
	ds_read_b128 v[172:175], v106 offset:51200
	ds_read_b128 v[176:179], v106 offset:52224
	ds_read_b128 v[180:183], v106 offset:53248
	ds_read_b128 v[184:187], v106 offset:54272
	ds_read_b128 v[188:191], v106 offset:55296
	ds_read_b128 v[192:195], v106 offset:56320
	global_load_lds_dwordx4 v[138:139], off
	v_lshl_add_u64 v[138:139], v[214:215], 0, s[52:53]
	s_mov_b32 m0, s37
	s_nop 0
	global_load_lds_dwordx4 v[138:139], off
	s_barrier
	s_waitcnt lgkmcnt(0)
	s_setprio 1
	s_waitcnt lgkmcnt(0)
	v_mfma_f32_16x16x32_bf16 v[148:151], v[88:91], v[134:137], v[148:151]
	v_mfma_f32_16x16x32_bf16 v[152:155], v[124:127], v[134:137], v[152:155]
	v_mfma_f32_16x16x32_bf16 v[156:159], v[88:91], v[172:175], v[156:159]
	v_mfma_f32_16x16x32_bf16 v[160:163], v[124:127], v[172:175], v[160:163]
	v_mfma_f32_16x16x32_bf16 v[164:167], v[88:91], v[180:183], v[164:167]
	v_mfma_f32_16x16x32_bf16 v[168:171], v[124:127], v[180:183], v[168:171]
	v_mfma_f32_16x16x32_bf16 v[0:3], v[88:91], v[188:191], v[0:3]
	v_mfma_f32_16x16x32_bf16 v[4:7], v[124:127], v[188:191], v[4:7]
	v_mfma_f32_16x16x32_bf16 v[148:151], v[92:95], v[144:147], v[148:151]
	v_mfma_f32_16x16x32_bf16 v[152:155], v[130:133], v[144:147], v[152:155]
	v_mfma_f32_16x16x32_bf16 v[156:159], v[92:95], v[176:179], v[156:159]
	v_mfma_f32_16x16x32_bf16 v[160:163], v[130:133], v[176:179], v[160:163]
	v_mfma_f32_16x16x32_bf16 v[164:167], v[92:95], v[184:187], v[164:167]
	v_mfma_f32_16x16x32_bf16 v[168:171], v[130:133], v[184:187], v[168:171]
	v_mfma_f32_16x16x32_bf16 v[0:3], v[92:95], v[192:195], v[0:3]
	v_mfma_f32_16x16x32_bf16 v[4:7], v[130:133], v[192:195], v[4:7]
	s_setprio 0
	s_barrier
	s_add_u32 s52, s18, 0x10180
	s_addc_u32 s53, s19, 0
	s_add_i32 s19, s51, s5
	v_lshl_add_u64 v[88:89], s[52:53], 0, v[98:99]
	s_mov_b32 m0, s19
	s_add_i32 s18, s19, 0x2000
	global_load_lds_dwordx4 v[88:89], off
	v_lshl_add_u64 v[88:89], s[52:53], 0, v[96:97]
	s_mov_b32 m0, s18
	s_nop 0
	global_load_lds_dwordx4 v[88:89], off
	s_waitcnt vmcnt(6)
	s_barrier
	s_setprio 1
	v_mfma_f32_16x16x32_bf16 v[8:11], v[196:199], v[134:137], v[8:11]
	v_mfma_f32_16x16x32_bf16 v[12:15], v[204:207], v[134:137], v[12:15]
	v_mfma_f32_16x16x32_bf16 v[44:47], v[196:199], v[172:175], v[44:47]
	v_mfma_f32_16x16x32_bf16 v[88:91], v[204:207], v[172:175], v[112:115]
	v_mfma_f32_16x16x32_bf16 v[92:95], v[196:199], v[180:183], v[116:119]
	v_mfma_f32_16x16x32_bf16 v[112:115], v[204:207], v[180:183], v[120:123]
	v_mfma_f32_16x16x32_bf16 v[80:83], v[196:199], v[188:191], v[80:83]
	v_mfma_f32_16x16x32_bf16 v[84:87], v[204:207], v[188:191], v[84:87]
	v_mfma_f32_16x16x32_bf16 v[8:11], v[200:203], v[144:147], v[8:11]
	v_mfma_f32_16x16x32_bf16 v[12:15], v[208:211], v[144:147], v[12:15]
	v_mfma_f32_16x16x32_bf16 v[44:47], v[200:203], v[176:179], v[44:47]
	v_mfma_f32_16x16x32_bf16 v[88:91], v[208:211], v[176:179], v[88:91]
	v_mfma_f32_16x16x32_bf16 v[92:95], v[200:203], v[184:187], v[92:95]
	v_mfma_f32_16x16x32_bf16 v[112:115], v[208:211], v[184:187], v[112:115]
	v_mfma_f32_16x16x32_bf16 v[80:83], v[200:203], v[192:195], v[80:83]
	v_mfma_f32_16x16x32_bf16 v[84:87], v[208:211], v[192:195], v[84:87]
	s_setprio 0
	s_barrier
	ds_read_b128 v[116:119], v107
	ds_read_b128 v[120:123], v107 offset:1024
	ds_read_b128 v[124:127], v107 offset:2048
	ds_read_b128 v[130:133], v107 offset:3072
	s_add_u32 s34, s34, 0x10180
	s_addc_u32 s35, s35, 0
	s_mov_b32 m0, s16
	v_lshl_add_u64 v[138:139], s[34:35], 0, v[98:99]
	ds_read_b128 v[134:137], v106
	ds_read_b128 v[144:147], v106 offset:1024
	ds_read_b128 v[172:175], v106 offset:2048
	ds_read_b128 v[176:179], v106 offset:3072
	ds_read_b128 v[180:183], v106 offset:4096
	ds_read_b128 v[184:187], v106 offset:5120
	ds_read_b128 v[188:191], v106 offset:6144
	ds_read_b128 v[192:195], v106 offset:7168
	global_load_lds_dwordx4 v[138:139], off
	v_lshl_add_u64 v[138:139], s[34:35], 0, v[96:97]
	s_mov_b32 m0, s13
	s_nop 0
	global_load_lds_dwordx4 v[138:139], off
	s_waitcnt lgkmcnt(8)
	s_barrier
	s_waitcnt lgkmcnt(0)
	s_setprio 1
	s_waitcnt lgkmcnt(0)
	v_mfma_f32_16x16x32_bf16 v[64:67], v[116:119], v[180:183], v[64:67]
	v_mfma_f32_16x16x32_bf16 v[196:199], v[120:123], v[184:187], v[64:67]
	v_mfma_f32_16x16x32_bf16 v[64:67], v[124:127], v[180:183], v[68:71]
	v_mfma_f32_16x16x32_bf16 v[68:71], v[130:133], v[184:187], v[64:67]
	v_mfma_f32_16x16x32_bf16 v[64:67], v[116:119], v[188:191], v[72:75]
	v_mfma_f32_16x16x32_bf16 v[48:51], v[116:119], v[134:137], v[48:51]
	v_mfma_f32_16x16x32_bf16 v[52:55], v[124:127], v[134:137], v[52:55]
	v_mfma_f32_16x16x32_bf16 v[56:59], v[116:119], v[172:175], v[56:59]
	v_mfma_f32_16x16x32_bf16 v[60:63], v[124:127], v[172:175], v[60:63]
	v_mfma_f32_16x16x32_bf16 v[200:203], v[120:123], v[192:195], v[64:67]
	v_mfma_f32_16x16x32_bf16 v[64:67], v[124:127], v[188:191], v[76:79]
	v_mfma_f32_16x16x32_bf16 v[48:51], v[120:123], v[144:147], v[48:51]
	v_mfma_f32_16x16x32_bf16 v[52:55], v[130:133], v[144:147], v[52:55]
	v_mfma_f32_16x16x32_bf16 v[56:59], v[120:123], v[176:179], v[56:59]
	v_mfma_f32_16x16x32_bf16 v[60:63], v[130:133], v[176:179], v[60:63]
	v_mfma_f32_16x16x32_bf16 v[76:79], v[130:133], v[192:195], v[64:67]
	s_setprio 0
	s_barrier
	s_mov_b32 m0, vcc_hi
	v_lshl_add_u64 v[138:139], s[14:15], 0, v[98:99]
	ds_read_b128 v[64:67], v128
	ds_read_b128 v[72:75], v128 offset:1024
	ds_read_b128 v[204:207], v128 offset:2048
	ds_read_b128 v[208:211], v128 offset:3072
	global_load_lds_dwordx4 v[138:139], off
	v_lshl_add_u64 v[140:141], s[14:15], 0, v[96:97]
	s_mov_b32 m0, s31
	s_nop 0
	global_load_lds_dwordx4 v[140:141], off
	s_barrier
	s_waitcnt lgkmcnt(0)
	s_setprio 1
	s_waitcnt lgkmcnt(0)
	v_mfma_f32_16x16x32_bf16 v[32:35], v[204:207], v[180:183], v[32:35]
	v_mfma_f32_16x16x32_bf16 v[108:111], v[64:67], v[134:137], v[108:111]
	v_mfma_f32_16x16x32_bf16 v[16:19], v[204:207], v[134:137], v[16:19]
	v_mfma_f32_16x16x32_bf16 v[134:137], v[208:211], v[184:187], v[32:35]
	v_mfma_f32_16x16x32_bf16 v[32:35], v[64:67], v[188:191], v[36:39]
	v_mfma_f32_16x16x32_bf16 v[108:111], v[72:75], v[144:147], v[108:111]
	v_mfma_f32_16x16x32_bf16 v[16:19], v[208:211], v[144:147], v[16:19]
	v_mfma_f32_16x16x32_bf16 v[20:23], v[64:67], v[172:175], v[20:23]
	v_mfma_f32_16x16x32_bf16 v[24:27], v[204:207], v[172:175], v[24:27]
	v_mfma_f32_16x16x32_bf16 v[28:31], v[64:67], v[180:183], v[28:31]
	v_mfma_f32_16x16x32_bf16 v[144:147], v[72:75], v[192:195], v[32:35]
	v_mfma_f32_16x16x32_bf16 v[32:35], v[204:207], v[188:191], v[40:43]
	v_mfma_f32_16x16x32_bf16 v[20:23], v[72:75], v[176:179], v[20:23]
	v_mfma_f32_16x16x32_bf16 v[24:27], v[208:211], v[176:179], v[24:27]
	v_mfma_f32_16x16x32_bf16 v[28:31], v[72:75], v[184:187], v[28:31]
	v_mfma_f32_16x16x32_bf16 v[172:175], v[208:211], v[192:195], v[32:35]
	s_setprio 0
	s_mov_b32 m0, s20
	v_lshl_add_u64 v[232:233], s[44:45], 0, v[98:99]
	s_barrier
	ds_read_b128 v[32:35], v106 offset:16384
	ds_read_b128 v[36:39], v106 offset:17408
	ds_read_b128 v[40:43], v106 offset:18432
	ds_read_b128 v[176:179], v106 offset:19456
	ds_read_b128 v[180:183], v106 offset:20480
	ds_read_b128 v[184:187], v106 offset:21504
	ds_read_b128 v[188:191], v106 offset:22528
	ds_read_b128 v[192:195], v106 offset:23552
	global_load_lds_dwordx4 v[232:233], off
	v_lshl_add_u64 v[240:241], s[44:45], 0, v[96:97]
	s_mov_b32 m0, s17
	s_nop 0
	global_load_lds_dwordx4 v[240:241], off
	s_barrier
	s_waitcnt lgkmcnt(0)
	s_setprio 1
	s_waitcnt lgkmcnt(0)
	v_mfma_f32_16x16x32_bf16 v[0:3], v[116:119], v[188:191], v[0:3]
	v_mfma_f32_16x16x32_bf16 v[148:151], v[116:119], v[32:35], v[148:151]
	v_mfma_f32_16x16x32_bf16 v[152:155], v[124:127], v[32:35], v[152:155]
	v_mfma_f32_16x16x32_bf16 v[156:159], v[116:119], v[40:43], v[156:159]
	v_mfma_f32_16x16x32_bf16 v[160:163], v[124:127], v[40:43], v[160:163]
	v_mfma_f32_16x16x32_bf16 v[164:167], v[116:119], v[180:183], v[164:167]
	v_mfma_f32_16x16x32_bf16 v[168:171], v[124:127], v[180:183], v[168:171]
	v_mfma_f32_16x16x32_bf16 v[116:119], v[120:123], v[192:195], v[0:3]
	v_mfma_f32_16x16x32_bf16 v[0:3], v[124:127], v[188:191], v[4:7]
	v_mfma_f32_16x16x32_bf16 v[148:151], v[120:123], v[36:39], v[148:151]
	v_mfma_f32_16x16x32_bf16 v[152:155], v[130:133], v[36:39], v[152:155]
	v_mfma_f32_16x16x32_bf16 v[156:159], v[120:123], v[176:179], v[156:159]
	v_mfma_f32_16x16x32_bf16 v[160:163], v[130:133], v[176:179], v[160:163]
	v_mfma_f32_16x16x32_bf16 v[164:167], v[120:123], v[184:187], v[164:167]
	v_mfma_f32_16x16x32_bf16 v[168:171], v[130:133], v[184:187], v[168:171]
	v_mfma_f32_16x16x32_bf16 v[120:123], v[130:133], v[192:195], v[0:3]
	s_setprio 0
	s_barrier
	s_add_u32 s34, s14, 0x10000
	s_addc_u32 s35, s15, 0
	s_mov_b32 m0, vcc_lo
	v_lshl_add_u64 v[0:1], s[34:35], 0, v[98:99]
	global_load_lds_dwordx4 v[0:1], off
	v_lshl_add_u64 v[0:1], s[34:35], 0, v[96:97]
	s_mov_b32 m0, s48
	s_nop 0
	global_load_lds_dwordx4 v[0:1], off
	s_waitcnt vmcnt(6)
	s_barrier
	s_setprio 1
	v_mfma_f32_16x16x32_bf16 v[0:3], v[64:67], v[32:35], v[8:11]
	v_mfma_f32_16x16x32_bf16 v[124:127], v[72:75], v[36:39], v[0:3]
	v_mfma_f32_16x16x32_bf16 v[0:3], v[204:207], v[32:35], v[12:15]
	v_mfma_f32_16x16x32_bf16 v[130:133], v[208:211], v[36:39], v[0:3]
	v_mfma_f32_16x16x32_bf16 v[0:3], v[64:67], v[40:43], v[44:47]
	v_mfma_f32_16x16x32_bf16 v[212:215], v[72:75], v[176:179], v[0:3]
	v_mfma_f32_16x16x32_bf16 v[0:3], v[204:207], v[40:43], v[88:91]
	v_mfma_f32_16x16x32_bf16 v[176:179], v[208:211], v[176:179], v[0:3]
	v_mfma_f32_16x16x32_bf16 v[0:3], v[64:67], v[180:183], v[92:95]
	v_mfma_f32_16x16x32_bf16 v[216:219], v[72:75], v[184:187], v[0:3]
	v_mfma_f32_16x16x32_bf16 v[0:3], v[204:207], v[180:183], v[112:115]
	v_mfma_f32_16x16x32_bf16 v[112:115], v[208:211], v[184:187], v[0:3]
	v_mfma_f32_16x16x32_bf16 v[0:3], v[64:67], v[188:191], v[80:83]
	v_mfma_f32_16x16x32_bf16 v[180:183], v[72:75], v[192:195], v[0:3]
	v_mfma_f32_16x16x32_bf16 v[0:3], v[204:207], v[188:191], v[84:87]
	v_mfma_f32_16x16x32_bf16 v[184:187], v[208:211], v[192:195], v[0:3]
	s_setprio 0
	s_barrier
	ds_read_b128 v[84:87], v143
	ds_read_b128 v[92:95], v143 offset:1024
	ds_read_b128 v[188:191], v143 offset:2048
	ds_read_b128 v[192:195], v143 offset:3072
	s_add_u32 s34, s44, 0x10000
	s_addc_u32 s35, s45, 0
	s_mov_b32 m0, s24
	v_lshl_add_u64 v[0:1], s[34:35], 0, v[98:99]
	ds_read_b128 v[4:7], v106 offset:32768
	ds_read_b128 v[12:15], v106 offset:33792
	ds_read_b128 v[36:39], v106 offset:34816
	ds_read_b128 v[44:47], v106 offset:35840
	ds_read_b128 v[80:83], v106 offset:36864
	ds_read_b128 v[88:91], v106 offset:37888
	ds_read_b128 v[204:207], v106 offset:38912
	ds_read_b128 v[208:211], v106 offset:39936
	global_load_lds_dwordx4 v[0:1], off
	v_lshl_add_u64 v[0:1], s[34:35], 0, v[96:97]
	s_mov_b32 m0, s25
	s_nop 0
	global_load_lds_dwordx4 v[0:1], off
	s_waitcnt lgkmcnt(8)
	s_barrier
	s_waitcnt lgkmcnt(0)
	s_setprio 1
	s_waitcnt lgkmcnt(0)
	v_mfma_f32_16x16x32_bf16 v[0:3], v[84:87], v[4:7], v[48:51]
	v_mfma_f32_16x16x32_bf16 v[220:223], v[92:95], v[12:15], v[0:3]
	v_mfma_f32_16x16x32_bf16 v[0:3], v[188:191], v[4:7], v[52:55]
	v_mfma_f32_16x16x32_bf16 v[224:227], v[192:195], v[12:15], v[0:3]
	v_mfma_f32_16x16x32_bf16 v[0:3], v[84:87], v[36:39], v[56:59]
	v_mfma_f32_16x16x32_bf16 v[72:75], v[92:95], v[44:47], v[0:3]
	v_mfma_f32_16x16x32_bf16 v[0:3], v[188:191], v[36:39], v[60:63]
	v_mfma_f32_16x16x32_bf16 v[64:67], v[192:195], v[44:47], v[0:3]
	v_mfma_f32_16x16x32_bf16 v[0:3], v[84:87], v[80:83], v[196:199]
	v_mfma_f32_16x16x32_bf16 v[40:43], v[92:95], v[88:91], v[0:3]
	v_mfma_f32_16x16x32_bf16 v[0:3], v[188:191], v[80:83], v[68:71]
	v_mfma_f32_16x16x32_bf16 v[32:35], v[192:195], v[88:91], v[0:3]
	v_mfma_f32_16x16x32_bf16 v[0:3], v[84:87], v[204:207], v[200:203]
	v_mfma_f32_16x16x32_bf16 v[8:11], v[92:95], v[208:211], v[0:3]
	v_mfma_f32_16x16x32_bf16 v[0:3], v[188:191], v[204:207], v[76:79]
	v_mfma_f32_16x16x32_bf16 v[0:3], v[192:195], v[208:211], v[0:3]
	s_setprio 0
	s_barrier
	s_mov_b32 m0, s50
	v_lshl_add_u64 v[48:49], v[138:139], 0, s[28:29]
	ds_read_b128 v[196:199], v236
	ds_read_b128 v[200:203], v236 offset:1024
	ds_read_b128 v[228:231], v236 offset:2048
	ds_read_b128 v[236:239], v236 offset:3072
	global_load_lds_dwordx4 v[48:49], off
	v_lshl_add_u64 v[48:49], v[140:141], 0, s[28:29]
	s_mov_b32 m0, s49
	s_nop 0
	global_load_lds_dwordx4 v[48:49], off
	s_barrier
	s_waitcnt lgkmcnt(0)
	s_setprio 1
	s_waitcnt lgkmcnt(0)
	v_mfma_f32_16x16x32_bf16 v[48:51], v[196:199], v[4:7], v[108:111]
	v_mfma_f32_16x16x32_bf16 v[4:7], v[228:231], v[4:7], v[16:19]
	v_mfma_f32_16x16x32_bf16 v[244:247], v[236:239], v[12:15], v[4:7]
	v_mfma_f32_16x16x32_bf16 v[4:7], v[196:199], v[36:39], v[20:23]
	v_mfma_f32_16x16x32_bf16 v[76:79], v[200:203], v[44:47], v[4:7]
	v_mfma_f32_16x16x32_bf16 v[4:7], v[228:231], v[36:39], v[24:27]
	v_mfma_f32_16x16x32_bf16 v[68:71], v[236:239], v[44:47], v[4:7]
	v_mfma_f32_16x16x32_bf16 v[4:7], v[196:199], v[80:83], v[28:31]
	v_mfma_f32_16x16x32_bf16 v[44:47], v[200:203], v[88:91], v[4:7]
	v_mfma_f32_16x16x32_bf16 v[4:7], v[228:231], v[80:83], v[134:137]
	v_mfma_f32_16x16x32_bf16 v[36:39], v[236:239], v[88:91], v[4:7]
	v_mfma_f32_16x16x32_bf16 v[4:7], v[196:199], v[204:207], v[144:147]
	v_mfma_f32_16x16x32_bf16 v[108:111], v[200:203], v[12:15], v[48:51]
	v_mfma_f32_16x16x32_bf16 v[12:15], v[200:203], v[208:211], v[4:7]
	v_mfma_f32_16x16x32_bf16 v[4:7], v[228:231], v[204:207], v[172:175]
	v_mfma_f32_16x16x32_bf16 v[4:7], v[236:239], v[208:211], v[4:7]
	s_setprio 0
	s_mov_b32 m0, s36
	v_lshl_add_u64 v[16:17], v[232:233], 0, s[28:29]
	s_barrier
	ds_read_b128 v[20:23], v106 offset:49152
	ds_read_b128 v[28:31], v106 offset:50176
	ds_read_b128 v[52:55], v106 offset:51200
	ds_read_b128 v[60:63], v106 offset:52224
	ds_read_b128 v[134:137], v106 offset:53248
	ds_read_b128 v[144:147], v106 offset:54272
	ds_read_b128 v[172:175], v106 offset:55296
	ds_read_b128 v[204:207], v106 offset:56320
	global_load_lds_dwordx4 v[16:17], off
	v_lshl_add_u64 v[16:17], v[240:241], 0, s[28:29]
	s_mov_b32 m0, s37
	s_nop 0
	global_load_lds_dwordx4 v[16:17], off
	s_barrier
	s_waitcnt lgkmcnt(0)
	s_setprio 1
	s_waitcnt lgkmcnt(0)
	v_mfma_f32_16x16x32_bf16 v[16:19], v[84:87], v[20:23], v[148:151]
	v_mfma_f32_16x16x32_bf16 v[148:151], v[92:95], v[28:31], v[16:19]
	v_mfma_f32_16x16x32_bf16 v[16:19], v[188:191], v[20:23], v[152:155]
	v_mfma_f32_16x16x32_bf16 v[152:155], v[192:195], v[28:31], v[16:19]
	v_mfma_f32_16x16x32_bf16 v[16:19], v[84:87], v[52:55], v[156:159]
	v_mfma_f32_16x16x32_bf16 v[88:91], v[92:95], v[60:63], v[16:19]
	v_mfma_f32_16x16x32_bf16 v[16:19], v[188:191], v[52:55], v[160:163]
	v_mfma_f32_16x16x32_bf16 v[80:83], v[192:195], v[60:63], v[16:19]
	v_mfma_f32_16x16x32_bf16 v[16:19], v[84:87], v[134:137], v[164:167]
	v_mfma_f32_16x16x32_bf16 v[56:59], v[92:95], v[144:147], v[16:19]
	v_mfma_f32_16x16x32_bf16 v[16:19], v[188:191], v[134:137], v[168:171]
	v_mfma_f32_16x16x32_bf16 v[48:51], v[192:195], v[144:147], v[16:19]
	v_mfma_f32_16x16x32_bf16 v[16:19], v[84:87], v[172:175], v[116:119]
	v_mfma_f32_16x16x32_bf16 v[24:27], v[92:95], v[204:207], v[16:19]
	v_mfma_f32_16x16x32_bf16 v[16:19], v[188:191], v[172:175], v[120:123]
	v_mfma_f32_16x16x32_bf16 v[16:19], v[192:195], v[204:207], v[16:19]
	s_setprio 0
	s_barrier
	s_add_u32 s14, s14, 0x10080
	s_addc_u32 s15, s15, 0
	s_mov_b32 m0, s19
	v_lshl_add_u64 v[84:85], s[14:15], 0, v[98:99]
	global_load_lds_dwordx4 v[84:85], off
	v_lshl_add_u64 v[84:85], s[14:15], 0, v[96:97]
	s_mov_b32 m0, s18
	s_nop 0
	global_load_lds_dwordx4 v[84:85], off
	s_waitcnt vmcnt(6)
	s_barrier
	s_setprio 1
	v_mfma_f32_16x16x32_bf16 v[84:87], v[196:199], v[20:23], v[124:127]
	v_mfma_f32_16x16x32_bf16 v[20:23], v[228:231], v[20:23], v[130:133]
	v_mfma_f32_16x16x32_bf16 v[120:123], v[236:239], v[28:31], v[20:23]
	v_mfma_f32_16x16x32_bf16 v[20:23], v[196:199], v[52:55], v[212:215]
	v_mfma_f32_16x16x32_bf16 v[92:95], v[200:203], v[60:63], v[20:23]
	v_mfma_f32_16x16x32_bf16 v[20:23], v[228:231], v[52:55], v[176:179]
	v_mfma_f32_16x16x32_bf16 v[116:119], v[200:203], v[28:31], v[84:87]
	v_mfma_f32_16x16x32_bf16 v[84:87], v[236:239], v[60:63], v[20:23]
	v_mfma_f32_16x16x32_bf16 v[20:23], v[196:199], v[134:137], v[216:219]
	v_mfma_f32_16x16x32_bf16 v[60:63], v[200:203], v[144:147], v[20:23]
	v_mfma_f32_16x16x32_bf16 v[20:23], v[228:231], v[134:137], v[112:115]
	v_mfma_f32_16x16x32_bf16 v[52:55], v[236:239], v[144:147], v[20:23]
	v_mfma_f32_16x16x32_bf16 v[20:23], v[196:199], v[172:175], v[180:183]
	v_mfma_f32_16x16x32_bf16 v[28:31], v[200:203], v[204:207], v[20:23]
	v_mfma_f32_16x16x32_bf16 v[20:23], v[228:231], v[172:175], v[184:187]
	v_mfma_f32_16x16x32_bf16 v[20:23], v[236:239], v[204:207], v[20:23]
	s_branch .Lfa2_x
	s_nop 0
	s_nop 0
	s_nop 0
	s_nop 0
.Lfa2_xd:
	v_lshl_add_u64 v[132:133], v[128:129], 1, s[14:15]
	v_pk_mul_f32 v[130:131], v[220:221], v[114:115]
	v_pk_mul_f32 v[134:135], v[222:223], v[126:127]
	v_pk_fma_f32 v[130:131], v[148:149], v[112:113], v[130:131] neg_lo:[0,0,1] neg_hi:[0,0,1]
	v_pk_fma_f32 v[134:135], v[150:151], v[124:125], v[134:135] neg_lo:[0,0,1] neg_hi:[0,0,1]
	v_cvt_pk_bf16_f32 v190, v130, v131
	v_cvt_pk_bf16_f32 v191, v134, v135
	v_lshl_add_u64 v[132:133], v[132:133], 0, v[196:197]
	s_nop 0
	v_permlane16_swap_b32_e32 v188, v190
	v_permlane16_swap_b32_e32 v189, v191
	global_store_dwordx4 v[132:133], v[188:191], off
	v_pk_mul_f32 v[130:131], v[116:117], v[114:115]
	v_pk_mul_f32 v[132:133], v[118:119], v[126:127]
	v_add_u32_e32 v107, s92, v136
	v_pk_fma_f32 v[130:131], v[108:109], v[112:113], v[130:131]
	v_pk_fma_f32 v[132:133], v[110:111], v[124:125], v[132:133]
	v_pk_mul_f32 v[108:109], v[108:109], v[114:115]
	v_pk_mul_f32 v[110:111], v[110:111], v[126:127]
	v_lshl_or_b32 v128, v107, 5, v102
	v_pk_fma_f32 v[108:109], v[116:117], v[112:113], v[108:109] neg_lo:[0,0,1] neg_hi:[0,0,1]
	v_pk_fma_f32 v[110:111], v[118:119], v[124:125], v[110:111] neg_lo:[0,0,1] neg_hi:[0,0,1]
	v_cvt_pk_bf16_f32 v192, v130, v131
	v_cvt_pk_bf16_f32 v193, v132, v133
	v_lshl_add_u64 v[132:133], v[128:129], 1, s[14:15]
	v_cvt_pk_bf16_f32 v194, v108, v109
	v_cvt_pk_bf16_f32 v195, v110, v111
	v_lshl_add_u64 v[132:133], v[132:133], 0, v[196:197]
	s_nop 0
	v_permlane16_swap_b32_e32 v192, v194
	v_permlane16_swap_b32_e32 v193, v195
	global_store_dwordx4 v[132:133], v[192:195], off
	v_add_u32_e32 v107, s47, v136
	v_pk_mul_f32 v[108:109], v[152:153], v[114:115]
	v_pk_mul_f32 v[110:111], v[154:155], v[126:127]
	v_lshl_or_b32 v128, v107, 5, v102
	v_pk_fma_f32 v[108:109], v[224:225], v[112:113], v[108:109]
	v_pk_fma_f32 v[110:111], v[226:227], v[124:125], v[110:111]
	v_cvt_pk_bf16_f32 v188, v108, v109
	v_cvt_pk_bf16_f32 v189, v110, v111
	v_lshl_add_u64 v[110:111], v[128:129], 1, s[14:15]
	v_pk_mul_f32 v[108:109], v[224:225], v[114:115]
	v_pk_mul_f32 v[116:117], v[226:227], v[126:127]
	v_pk_fma_f32 v[108:109], v[152:153], v[112:113], v[108:109] neg_lo:[0,0,1] neg_hi:[0,0,1]
	v_pk_fma_f32 v[116:117], v[154:155], v[124:125], v[116:117] neg_lo:[0,0,1] neg_hi:[0,0,1]
	v_cvt_pk_bf16_f32 v190, v108, v109
	v_cvt_pk_bf16_f32 v191, v116, v117
	v_lshl_add_u64 v[110:111], v[110:111], 0, v[196:197]
	s_nop 0
	v_permlane16_swap_b32_e32 v188, v190
	v_permlane16_swap_b32_e32 v189, v191
	global_store_dwordx4 v[110:111], v[188:191], off
	v_add_u32_e32 v107, s4, v136
	v_pk_mul_f32 v[108:109], v[120:121], v[114:115]
	v_pk_mul_f32 v[110:111], v[122:123], v[126:127]
	v_lshl_or_b32 v128, v107, 5, v102
	v_pk_fma_f32 v[108:109], v[244:245], v[112:113], v[108:109]
	v_pk_fma_f32 v[110:111], v[246:247], v[124:125], v[110:111]
	v_cvt_pk_bf16_f32 v192, v108, v109
	v_cvt_pk_bf16_f32 v193, v110, v111
	v_lshl_add_u64 v[110:111], v[128:129], 1, s[14:15]
	v_pk_mul_f32 v[108:109], v[244:245], v[114:115]
	s_nop 0
	v_pk_fma_f32 v[108:109], v[120:121], v[112:113], v[108:109] neg_lo:[0,0,1] neg_hi:[0,0,1]
	v_pk_mul_f32 v[112:113], v[246:247], v[126:127]
	v_cvt_pk_bf16_f32 v194, v108, v109
	v_pk_fma_f32 v[112:113], v[122:123], v[124:125], v[112:113] neg_lo:[0,0,1] neg_hi:[0,0,1]
	s_nop 0
	v_cvt_pk_bf16_f32 v195, v112, v113
	v_lshl_add_u64 v[110:111], v[110:111], 0, v[196:197]
	s_nop 0
	v_permlane16_swap_b32_e32 v192, v194
	v_permlane16_swap_b32_e32 v193, v195
	global_store_dwordx4 v[110:111], v[192:195], off
	v_mov_b32_e32 v107, v103
	s_nop 0
	v_mul_lo_u32 v108, v107, v102
	v_cvt_f32_i32_e32 v109, v108
	v_add_u32_e32 v111, v108, v107
	v_cvt_f32_i32_e32 v112, v111
	v_lshl_add_u32 v120, v107, 10, s1
	v_mul_f32_e32 v108, 0x3b490fdb, v109
	v_mul_f32_e32 v109, 0.15915494, v108
	v_cos_f32_e32 v108, v109
	v_sin_f32_e32 v110, v109
	v_mul_f32_e32 v109, 0x3b490fdb, v112
	v_add_u32_e32 v112, v111, v107
	v_add_u32_e32 v107, v112, v107
	v_cvt_f32_i32_e32 v113, v112
	v_cvt_f32_i32_e32 v107, v107
	v_mul_f32_e32 v111, 0.15915494, v109
	v_cos_f32_e32 v109, v111
	v_mul_f32_e32 v113, 0x3b490fdb, v113
	v_mul_f32_e32 v107, 0x3b490fdb, v107
	v_mul_f32_e32 v113, 0.15915494, v113
	v_mul_f32_e32 v107, 0.15915494, v107
	v_sin_f32_e32 v111, v111
	v_sin_f32_e32 v114, v113
	v_sin_f32_e32 v115, v107
	v_cos_f32_e32 v112, v113
	v_cos_f32_e32 v113, v107
	v_pk_mul_f32 v[116:117], v[88:89], v[110:111]
	v_pk_mul_f32 v[118:119], v[90:91], v[114:115]
	v_add_u32_e32 v107, s46, v120
	v_pk_fma_f32 v[116:117], v[72:73], v[108:109], v[116:117]
	v_pk_fma_f32 v[118:119], v[74:75], v[112:113], v[118:119]
	v_pk_mul_f32 v[72:73], v[72:73], v[110:111]
	v_pk_mul_f32 v[74:75], v[74:75], v[114:115]
	v_lshl_or_b32 v128, v107, 5, v102
	v_pk_fma_f32 v[72:73], v[88:89], v[108:109], v[72:73] neg_lo:[0,0,1] neg_hi:[0,0,1]
	v_pk_fma_f32 v[74:75], v[90:91], v[112:113], v[74:75] neg_lo:[0,0,1] neg_hi:[0,0,1]
	v_cvt_pk_bf16_f32 v188, v116, v117
	v_cvt_pk_bf16_f32 v189, v118, v119
	v_lshl_add_u64 v[118:119], v[128:129], 1, s[14:15]
	v_cvt_pk_bf16_f32 v190, v72, v73
	v_cvt_pk_bf16_f32 v191, v74, v75
	v_add_u32_e32 v72, s92, v120
	v_lshl_or_b32 v128, v72, 5, v102
	v_pk_mul_f32 v[72:73], v[92:93], v[110:111]
	v_pk_mul_f32 v[74:75], v[94:95], v[114:115]
	v_pk_fma_f32 v[72:73], v[76:77], v[108:109], v[72:73]
	v_pk_fma_f32 v[74:75], v[78:79], v[112:113], v[74:75]
	v_cvt_pk_bf16_f32 v192, v72, v73
	v_cvt_pk_bf16_f32 v193, v74, v75
	v_lshl_add_u64 v[74:75], v[128:129], 1, s[14:15]
	v_lshl_add_u64 v[118:119], v[118:119], 0, v[196:197]
	s_nop 0
	v_permlane16_swap_b32_e32 v188, v190
	v_permlane16_swap_b32_e32 v189, v191
	global_store_dwordx4 v[118:119], v[188:191], off
	v_pk_mul_f32 v[72:73], v[76:77], v[110:111]
	v_pk_mul_f32 v[76:77], v[78:79], v[114:115]
	v_pk_fma_f32 v[72:73], v[92:93], v[108:109], v[72:73] neg_lo:[0,0,1] neg_hi:[0,0,1]
	v_pk_fma_f32 v[76:77], v[94:95], v[112:113], v[76:77] neg_lo:[0,0,1] neg_hi:[0,0,1]
	v_cvt_pk_bf16_f32 v194, v72, v73
	v_cvt_pk_bf16_f32 v195, v76, v77
	v_lshl_add_u64 v[74:75], v[74:75], 0, v[196:197]
	s_nop 0
	v_permlane16_swap_b32_e32 v192, v194
	v_permlane16_swap_b32_e32 v193, v195
	global_store_dwordx4 v[74:75], v[192:195], off
	v_add_u32_e32 v72, s47, v120
	v_lshl_or_b32 v128, v72, 5, v102
	v_pk_mul_f32 v[72:73], v[80:81], v[110:111]
	v_pk_mul_f32 v[74:75], v[82:83], v[114:115]
	v_pk_fma_f32 v[72:73], v[64:65], v[108:109], v[72:73]
	v_pk_fma_f32 v[74:75], v[66:67], v[112:113], v[74:75]
	v_pk_mul_f32 v[64:65], v[64:65], v[110:111]
	v_pk_mul_f32 v[66:67], v[66:67], v[114:115]
	v_pk_fma_f32 v[64:65], v[80:81], v[108:109], v[64:65] neg_lo:[0,0,1] neg_hi:[0,0,1]
	v_pk_fma_f32 v[66:67], v[82:83], v[112:113], v[66:67] neg_lo:[0,0,1] neg_hi:[0,0,1]
	v_cvt_pk_bf16_f32 v188, v72, v73
	v_cvt_pk_bf16_f32 v189, v74, v75
	v_lshl_add_u64 v[74:75], v[128:129], 1, s[14:15]
	v_cvt_pk_bf16_f32 v190, v64, v65
	v_cvt_pk_bf16_f32 v191, v66, v67
	v_add_u32_e32 v64, s4, v120
	v_lshl_or_b32 v128, v64, 5, v102
	v_pk_mul_f32 v[64:65], v[84:85], v[110:111]
	v_pk_mul_f32 v[66:67], v[86:87], v[114:115]
	v_pk_fma_f32 v[64:65], v[68:69], v[108:109], v[64:65]
	v_pk_fma_f32 v[66:67], v[70:71], v[112:113], v[66:67]
	v_cvt_pk_bf16_f32 v192, v64, v65
	v_cvt_pk_bf16_f32 v193, v66, v67
	v_lshl_add_u64 v[66:67], v[128:129], 1, s[14:15]
	v_lshl_add_u64 v[74:75], v[74:75], 0, v[196:197]
	s_nop 0
	v_permlane16_swap_b32_e32 v188, v190
	v_permlane16_swap_b32_e32 v189, v191
	global_store_dwordx4 v[74:75], v[188:191], off
	v_pk_mul_f32 v[64:65], v[68:69], v[110:111]
	v_pk_mul_f32 v[68:69], v[70:71], v[114:115]
	v_pk_fma_f32 v[64:65], v[84:85], v[108:109], v[64:65] neg_lo:[0,0,1] neg_hi:[0,0,1]
	v_pk_fma_f32 v[68:69], v[86:87], v[112:113], v[68:69] neg_lo:[0,0,1] neg_hi:[0,0,1]
	v_cvt_pk_bf16_f32 v194, v64, v65
	v_cvt_pk_bf16_f32 v195, v68, v69
	v_lshl_add_u64 v[66:67], v[66:67], 0, v[196:197]
	s_nop 0
	v_permlane16_swap_b32_e32 v192, v194
	v_permlane16_swap_b32_e32 v193, v195
	global_store_dwordx4 v[66:67], v[192:195], off
	v_mov_b32_e32 v68, v104
	s_nop 0
	v_mul_lo_u32 v64, v68, v102
	v_cvt_f32_i32_e32 v65, v64
	v_add_u32_e32 v67, v64, v68
	v_cvt_f32_i32_e32 v69, v67
	v_lshl_add_u32 v76, v68, 10, s1
	v_mul_f32_e32 v64, 0x3b490fdb, v65
	v_mul_f32_e32 v65, 0.15915494, v64
	v_cos_f32_e32 v64, v65
	v_sin_f32_e32 v66, v65
	v_mul_f32_e32 v65, 0x3b490fdb, v69
	v_add_u32_e32 v69, v67, v68
	v_add_u32_e32 v68, v69, v68
	v_cvt_f32_i32_e32 v70, v69
	v_cvt_f32_i32_e32 v69, v68
	v_mul_f32_e32 v67, 0.15915494, v65
	v_cos_f32_e32 v65, v67
	v_mul_f32_e32 v70, 0x3b490fdb, v70
	v_mul_f32_e32 v69, 0x3b490fdb, v69
	v_mul_f32_e32 v70, 0.15915494, v70
	v_mul_f32_e32 v71, 0.15915494, v69
	v_sin_f32_e32 v67, v67
	v_cos_f32_e32 v68, v70
	v_sin_f32_e32 v70, v70
	v_cos_f32_e32 v69, v71
	v_sin_f32_e32 v71, v71
	v_add_u32_e32 v72, s46, v76
	v_lshl_or_b32 v128, v72, 5, v102
	v_pk_mul_f32 v[72:73], v[56:57], v[66:67]
	v_pk_mul_f32 v[74:75], v[58:59], v[70:71]
	v_pk_fma_f32 v[72:73], v[40:41], v[64:65], v[72:73]
	v_pk_fma_f32 v[74:75], v[42:43], v[68:69], v[74:75]
	v_pk_mul_f32 v[40:41], v[40:41], v[66:67]
	v_pk_mul_f32 v[42:43], v[42:43], v[70:71]
	v_pk_fma_f32 v[40:41], v[56:57], v[64:65], v[40:41] neg_lo:[0,0,1] neg_hi:[0,0,1]
	v_pk_fma_f32 v[42:43], v[58:59], v[68:69], v[42:43] neg_lo:[0,0,1] neg_hi:[0,0,1]
	v_cvt_pk_bf16_f32 v188, v72, v73
	v_cvt_pk_bf16_f32 v189, v74, v75
	v_lshl_add_u64 v[74:75], v[128:129], 1, s[14:15]
	v_cvt_pk_bf16_f32 v190, v40, v41
	v_cvt_pk_bf16_f32 v191, v42, v43
	v_add_u32_e32 v40, s92, v76
	v_lshl_or_b32 v128, v40, 5, v102
	v_pk_mul_f32 v[40:41], v[60:61], v[66:67]
	v_pk_mul_f32 v[42:43], v[62:63], v[70:71]
	v_pk_fma_f32 v[40:41], v[44:45], v[64:65], v[40:41]
	v_pk_fma_f32 v[42:43], v[46:47], v[68:69], v[42:43]
	v_cvt_pk_bf16_f32 v192, v40, v41
	v_cvt_pk_bf16_f32 v193, v42, v43
	v_lshl_add_u64 v[42:43], v[128:129], 1, s[14:15]
	v_lshl_add_u64 v[74:75], v[74:75], 0, v[196:197]
	s_nop 0
	v_permlane16_swap_b32_e32 v188, v190
	v_permlane16_swap_b32_e32 v189, v191
	global_store_dwordx4 v[74:75], v[188:191], off
	v_pk_mul_f32 v[40:41], v[44:45], v[66:67]
	v_pk_mul_f32 v[44:45], v[46:47], v[70:71]
	v_pk_fma_f32 v[40:41], v[60:61], v[64:65], v[40:41] neg_lo:[0,0,1] neg_hi:[0,0,1]
	v_pk_fma_f32 v[44:45], v[62:63], v[68:69], v[44:45] neg_lo:[0,0,1] neg_hi:[0,0,1]
	v_cvt_pk_bf16_f32 v194, v40, v41
	v_cvt_pk_bf16_f32 v195, v44, v45
	v_lshl_add_u64 v[42:43], v[42:43], 0, v[196:197]
	s_nop 0
	v_permlane16_swap_b32_e32 v192, v194
	v_permlane16_swap_b32_e32 v193, v195
	global_store_dwordx4 v[42:43], v[192:195], off
	v_add_u32_e32 v40, s47, v76
	v_lshl_or_b32 v128, v40, 5, v102
	v_pk_mul_f32 v[40:41], v[48:49], v[66:67]
	v_pk_mul_f32 v[42:43], v[50:51], v[70:71]
	v_pk_fma_f32 v[40:41], v[32:33], v[64:65], v[40:41]
	v_pk_fma_f32 v[42:43], v[34:35], v[68:69], v[42:43]
	v_pk_mul_f32 v[32:33], v[32:33], v[66:67]
	v_pk_mul_f32 v[34:35], v[34:35], v[70:71]
	v_pk_fma_f32 v[32:33], v[48:49], v[64:65], v[32:33] neg_lo:[0,0,1] neg_hi:[0,0,1]
	v_pk_fma_f32 v[34:35], v[50:51], v[68:69], v[34:35] neg_lo:[0,0,1] neg_hi:[0,0,1]
	v_cvt_pk_bf16_f32 v188, v40, v41
	v_cvt_pk_bf16_f32 v189, v42, v43
	v_lshl_add_u64 v[42:43], v[128:129], 1, s[14:15]
	v_cvt_pk_bf16_f32 v190, v32, v33
	v_cvt_pk_bf16_f32 v191, v34, v35
	v_add_u32_e32 v32, s4, v76
	v_lshl_or_b32 v128, v32, 5, v102
	v_pk_mul_f32 v[32:33], v[52:53], v[66:67]
	v_pk_mul_f32 v[34:35], v[54:55], v[70:71]
	v_pk_fma_f32 v[32:33], v[36:37], v[64:65], v[32:33]
	v_pk_fma_f32 v[34:35], v[38:39], v[68:69], v[34:35]
	v_cvt_pk_bf16_f32 v192, v32, v33
	v_cvt_pk_bf16_f32 v193, v34, v35
	v_lshl_add_u64 v[34:35], v[128:129], 1, s[14:15]
	v_lshl_add_u64 v[42:43], v[42:43], 0, v[196:197]
	s_nop 0
	v_permlane16_swap_b32_e32 v188, v190
	v_permlane16_swap_b32_e32 v189, v191
	global_store_dwordx4 v[42:43], v[188:191], off
	v_pk_mul_f32 v[32:33], v[36:37], v[66:67]
	v_pk_mul_f32 v[36:37], v[38:39], v[70:71]
	v_pk_fma_f32 v[32:33], v[52:53], v[64:65], v[32:33] neg_lo:[0,0,1] neg_hi:[0,0,1]
	v_pk_fma_f32 v[36:37], v[54:55], v[68:69], v[36:37] neg_lo:[0,0,1] neg_hi:[0,0,1]
	v_cvt_pk_bf16_f32 v194, v32, v33
	v_cvt_pk_bf16_f32 v195, v36, v37
	v_lshl_add_u64 v[34:35], v[34:35], 0, v[196:197]
	s_nop 0
	v_permlane16_swap_b32_e32 v192, v194
	v_permlane16_swap_b32_e32 v193, v195
	global_store_dwordx4 v[34:35], v[192:195], off
	v_mov_b32_e32 v36, v105
	s_nop 0
	v_mul_lo_u32 v32, v36, v102
	v_cvt_f32_i32_e32 v33, v32
	v_add_u32_e32 v35, v32, v36
	v_cvt_f32_i32_e32 v37, v35
	v_lshl_add_u32 v44, v36, 10, s1
	v_mul_f32_e32 v32, 0x3b490fdb, v33
	v_mul_f32_e32 v33, 0.15915494, v32
	v_cos_f32_e32 v32, v33
	v_sin_f32_e32 v34, v33
	v_mul_f32_e32 v33, 0x3b490fdb, v37
	v_add_u32_e32 v37, v35, v36
	v_add_u32_e32 v36, v37, v36
	v_cvt_f32_i32_e32 v38, v37
	v_cvt_f32_i32_e32 v37, v36
	v_mul_f32_e32 v35, 0.15915494, v33
	v_cos_f32_e32 v33, v35
	v_mul_f32_e32 v38, 0x3b490fdb, v38
	v_mul_f32_e32 v37, 0x3b490fdb, v37
	v_mul_f32_e32 v38, 0.15915494, v38
	v_mul_f32_e32 v39, 0.15915494, v37
	v_sin_f32_e32 v35, v35
	v_cos_f32_e32 v36, v38
	v_sin_f32_e32 v38, v38
	v_cos_f32_e32 v37, v39
	v_sin_f32_e32 v39, v39
	v_add_u32_e32 v40, s46, v44
	v_lshl_or_b32 v128, v40, 5, v102
	v_pk_mul_f32 v[40:41], v[24:25], v[34:35]
	v_pk_mul_f32 v[42:43], v[26:27], v[38:39]
	v_pk_fma_f32 v[40:41], v[8:9], v[32:33], v[40:41]
	v_pk_fma_f32 v[42:43], v[10:11], v[36:37], v[42:43]
	v_pk_mul_f32 v[8:9], v[8:9], v[34:35]
	v_pk_mul_f32 v[10:11], v[10:11], v[38:39]
	v_pk_fma_f32 v[8:9], v[24:25], v[32:33], v[8:9] neg_lo:[0,0,1] neg_hi:[0,0,1]
	v_pk_fma_f32 v[10:11], v[26:27], v[36:37], v[10:11] neg_lo:[0,0,1] neg_hi:[0,0,1]
	v_cvt_pk_bf16_f32 v188, v40, v41
	v_cvt_pk_bf16_f32 v189, v42, v43
	v_lshl_add_u64 v[42:43], v[128:129], 1, s[14:15]
	v_cvt_pk_bf16_f32 v190, v8, v9
	v_cvt_pk_bf16_f32 v191, v10, v11
	v_add_u32_e32 v8, s92, v44
	v_lshl_or_b32 v128, v8, 5, v102
	v_pk_mul_f32 v[8:9], v[28:29], v[34:35]
	v_pk_mul_f32 v[10:11], v[30:31], v[38:39]
	v_pk_fma_f32 v[8:9], v[12:13], v[32:33], v[8:9]
	v_pk_fma_f32 v[10:11], v[14:15], v[36:37], v[10:11]
	v_cvt_pk_bf16_f32 v192, v8, v9
	v_cvt_pk_bf16_f32 v193, v10, v11
	v_lshl_add_u64 v[10:11], v[128:129], 1, s[14:15]
	v_lshl_add_u64 v[42:43], v[42:43], 0, v[196:197]
	s_nop 0
	v_permlane16_swap_b32_e32 v188, v190
	v_permlane16_swap_b32_e32 v189, v191
	global_store_dwordx4 v[42:43], v[188:191], off
	v_pk_mul_f32 v[8:9], v[12:13], v[34:35]
	v_pk_mul_f32 v[12:13], v[14:15], v[38:39]
	v_pk_fma_f32 v[8:9], v[28:29], v[32:33], v[8:9] neg_lo:[0,0,1] neg_hi:[0,0,1]
	v_pk_fma_f32 v[12:13], v[30:31], v[36:37], v[12:13] neg_lo:[0,0,1] neg_hi:[0,0,1]
	v_cvt_pk_bf16_f32 v194, v8, v9
	v_cvt_pk_bf16_f32 v195, v12, v13
	v_lshl_add_u64 v[10:11], v[10:11], 0, v[196:197]
	s_nop 0
	v_permlane16_swap_b32_e32 v192, v194
	v_permlane16_swap_b32_e32 v193, v195
	global_store_dwordx4 v[10:11], v[192:195], off
	v_add_u32_e32 v8, s47, v44
	v_lshl_or_b32 v128, v8, 5, v102
	v_pk_mul_f32 v[8:9], v[16:17], v[34:35]
	v_pk_mul_f32 v[10:11], v[18:19], v[38:39]
	v_pk_fma_f32 v[8:9], v[0:1], v[32:33], v[8:9]
	v_pk_fma_f32 v[10:11], v[2:3], v[36:37], v[10:11]
	v_pk_mul_f32 v[0:1], v[0:1], v[34:35]
	v_pk_mul_f32 v[2:3], v[2:3], v[38:39]
	v_pk_fma_f32 v[0:1], v[16:17], v[32:33], v[0:1] neg_lo:[0,0,1] neg_hi:[0,0,1]
	v_pk_fma_f32 v[2:3], v[18:19], v[36:37], v[2:3] neg_lo:[0,0,1] neg_hi:[0,0,1]
	v_cvt_pk_bf16_f32 v188, v8, v9
	v_cvt_pk_bf16_f32 v189, v10, v11
	v_lshl_add_u64 v[10:11], v[128:129], 1, s[14:15]
	v_cvt_pk_bf16_f32 v190, v0, v1
	v_cvt_pk_bf16_f32 v191, v2, v3
	v_add_u32_e32 v0, s4, v44
	v_lshl_or_b32 v128, v0, 5, v102
	v_pk_mul_f32 v[0:1], v[20:21], v[34:35]
	v_pk_mul_f32 v[2:3], v[22:23], v[38:39]
	v_pk_fma_f32 v[0:1], v[4:5], v[32:33], v[0:1]
	v_pk_fma_f32 v[2:3], v[6:7], v[36:37], v[2:3]
	v_cvt_pk_bf16_f32 v192, v0, v1
	v_cvt_pk_bf16_f32 v193, v2, v3
	v_lshl_add_u64 v[2:3], v[128:129], 1, s[14:15]
	v_lshl_add_u64 v[10:11], v[10:11], 0, v[196:197]
	s_nop 0
	v_permlane16_swap_b32_e32 v188, v190
	v_permlane16_swap_b32_e32 v189, v191
	global_store_dwordx4 v[10:11], v[188:191], off
	v_pk_mul_f32 v[0:1], v[4:5], v[34:35]
	v_pk_mul_f32 v[4:5], v[6:7], v[38:39]
	v_pk_fma_f32 v[0:1], v[20:21], v[32:33], v[0:1] neg_lo:[0,0,1] neg_hi:[0,0,1]
	v_pk_fma_f32 v[4:5], v[22:23], v[36:37], v[4:5] neg_lo:[0,0,1] neg_hi:[0,0,1]
	v_cvt_pk_bf16_f32 v194, v0, v1
	v_cvt_pk_bf16_f32 v195, v4, v5
	v_lshl_add_u64 v[2:3], v[2:3], 0, v[196:197]
	s_nop 0
	v_permlane16_swap_b32_e32 v192, v194
	v_permlane16_swap_b32_e32 v193, v195
	global_store_dwordx4 v[2:3], v[192:195], off
	s_add_i32 s0, s0, s90
	s_andn2_b64 vcc, exec, s[38:39]
	s_mov_b32 s1, s12
	s_mov_b64 s[18:19], s[42:43]
	s_mov_b64 s[34:35], s[40:41]
	s_cbranch_vccz .LBB0_79

.Lnm_pro:
	v_lshl_add_u64 v[112:113], s[88:89], 0, v[36:37]
	v_lshl_add_u64 v[114:115], s[88:89], 0, v[58:59]
	v_add_co_u32_e32 v112, vcc, 0x8a80000, v112
	s_nop 0
	v_addc_co_u32_e32 v113, vcc, 0, v113, vcc
	global_load_dwordx4 v[0:3], v[114:115], off
	global_load_dwordx4 v[4:7], v[114:115], off offset:1024
	global_load_dwordx4 v[8:11], v[112:113], off
	global_load_dwordx4 v[12:15], v[112:113], off offset:1024
	s_branch .LBB0_318
	s_nop 0
	s_nop 0
	s_nop 0
	s_nop 0
	s_nop 0
	s_nop 0
	s_nop 0
	s_nop 0
	s_nop 0
	s_nop 0
	s_nop 0
	s_nop 0
	s_nop 0
	s_nop 0
	s_nop 0
	s_nop 0
	s_nop 0
	s_nop 0
	s_nop 0
	s_nop 0
	s_nop 0
	s_nop 0
	s_nop 0
	s_nop 0
	s_nop 0
	s_nop 0
	s_nop 0
	s_nop 0
	s_nop 0
	s_nop 0
	s_nop 0
	s_nop 0
	s_nop 0
	s_nop 0
	s_nop 0
	s_nop 0
	s_nop 0
	s_nop 0
	s_nop 0
	s_nop 0
	s_nop 0
	s_nop 0
	s_nop 0
	s_nop 0
	s_nop 0
	s_nop 0
	s_nop 0
	s_nop 0
	s_nop 0
	s_nop 0
	s_nop 0
	s_nop 0
	s_nop 0
	s_nop 0
	s_nop 0
	s_nop 0
	s_nop 0
	s_nop 0
	s_nop 0
	s_nop 0
	s_nop 0
	s_nop 0
	s_nop 0
	s_nop 0
	s_nop 0
	s_nop 0
	s_nop 0
	s_nop 0
	s_nop 0
	s_nop 0
	s_nop 0
	s_nop 0
	s_nop 0
	s_nop 0
	s_nop 0
	s_nop 0
	s_nop 0
	s_nop 0
	s_nop 0
	s_nop 0
	s_nop 0
	s_nop 0
	s_nop 0
	s_nop 0
	s_nop 0
	s_nop 0
	s_nop 0
	s_nop 0
	s_nop 0
	s_nop 0
	s_nop 0
	s_nop 0
	s_nop 0
	s_nop 0
	s_nop 0
	s_nop 0
	s_nop 0
	s_nop 0
	s_nop 0
	s_nop 0
	s_nop 0
	s_nop 0
	s_nop 0
	s_nop 0
	s_nop 0
	s_nop 0
	s_nop 0
	s_nop 0
	s_nop 0
	s_nop 0
	s_nop 0
	s_nop 0
	s_nop 0
	s_nop 0
	s_nop 0
	s_nop 0
	s_nop 0
	s_nop 0
	s_nop 0
	s_nop 0
	s_nop 0
	s_nop 0
	s_nop 0
	s_nop 0
	s_nop 0
	s_nop 0
	s_nop 0
	s_nop 0
	s_nop 0
	s_nop 0
	s_nop 0
	s_nop 0
	s_nop 0
	s_nop 0
	s_nop 0
	s_nop 0
	s_nop 0
	s_nop 0
	s_nop 0
	s_nop 0
	s_nop 0
	s_nop 0
	s_nop 0
	s_nop 0
	s_nop 0
	s_nop 0
	s_nop 0
	s_nop 0
	s_nop 0
	s_nop 0
	s_nop 0
	s_nop 0
	s_nop 0
	s_nop 0
	s_nop 0
	s_nop 0
	s_nop 0
	s_nop 0
	s_nop 0
	s_nop 0
	s_nop 0
	s_nop 0
	s_nop 0
	s_nop 0
	s_nop 0
	s_nop 0
	s_nop 0
	s_nop 0
	s_nop 0
	s_nop 0
	s_nop 0
	s_nop 0
	s_nop 0
	s_nop 0
	s_nop 0
	s_nop 0
	s_nop 0
	s_nop 0
	s_nop 0
	s_nop 0
	s_nop 0
	s_nop 0
	s_nop 0
	s_nop 0
	s_nop 0
	s_nop 0
	s_nop 0
	s_nop 0
	s_nop 0
	s_nop 0
	s_nop 0
	s_nop 0
	s_nop 0
	s_nop 0
	s_nop 0
	s_nop 0
	s_nop 0
	s_nop 0
	s_nop 0
	s_nop 0
	s_nop 0
	s_nop 0
	s_nop 0
	s_nop 0
	s_nop 0
	s_nop 0
	s_nop 0
	s_nop 0
	s_nop 0
	s_nop 0
	s_nop 0
	s_nop 0
	s_nop 0
	s_nop 0
	s_nop 0
	s_nop 0
	s_nop 0
	s_nop 0
	s_nop 0
	s_nop 0
	s_nop 0
	s_nop 0
	s_nop 0
	s_nop 0
	s_nop 0
	s_nop 0
	s_nop 0
	s_nop 0
	s_nop 0
	s_nop 0
	s_nop 0
	s_nop 0
	s_nop 0
	s_nop 0
	s_nop 0
	s_nop 0
	s_nop 0
	s_nop 0
	s_nop 0
	s_nop 0
	s_nop 0
	s_nop 0
	s_nop 0
	s_nop 0
	s_nop 0
	s_nop 0
	s_nop 0
	s_nop 0
	s_nop 0
	s_nop 0
	s_nop 0
	s_nop 0
	s_nop 0
	s_nop 0
	s_nop 0
	s_nop 0
	s_nop 0
	s_nop 0
	s_nop 0
	s_nop 0
	s_nop 0
	s_nop 0
	s_nop 0
	s_nop 0
	s_nop 0
	s_nop 0
	s_nop 0
	s_nop 0
	s_nop 0
	s_nop 0
	s_nop 0
	s_nop 0
	s_nop 0
	s_nop 0
	s_nop 0
	s_nop 0
	s_nop 0
	s_nop 0
	s_nop 0
	s_nop 0
	s_nop 0
	s_nop 0
	s_nop 0
	s_nop 0
	s_nop 0
	s_nop 0
	s_nop 0
	s_nop 0
	s_nop 0
	s_nop 0
	s_nop 0
	s_nop 0
	s_nop 0
	s_nop 0
	s_nop 0
	s_nop 0
	s_nop 0
	s_nop 0
	s_nop 0
	s_nop 0
	s_nop 0
	s_nop 0
	s_nop 0
	s_nop 0
	s_nop 0
	s_nop 0
	s_nop 0
	s_nop 0
	s_nop 0
	s_nop 0
	s_nop 0
	s_nop 0
	s_nop 0
	s_nop 0
	s_nop 0
	s_nop 0
	s_nop 0
	s_nop 0
	s_nop 0
	s_nop 0
	s_nop 0
	s_nop 0
	s_nop 0
	s_nop 0
	s_nop 0
	s_nop 0
	s_nop 0
	s_nop 0
	s_nop 0
	s_nop 0
	s_nop 0
	s_nop 0
	s_nop 0
	s_nop 0
	s_nop 0
	s_nop 0
	s_nop 0
	s_nop 0
	s_nop 0
	s_nop 0
	s_nop 0
	s_nop 0
	s_nop 0
	s_nop 0
	s_nop 0
	s_nop 0
	s_nop 0
	s_nop 0
	s_nop 0
	s_nop 0
	s_nop 0
	s_nop 0
	s_nop 0
	s_nop 0
	s_nop 0
	s_nop 0
	s_nop 0
	s_nop 0
	s_nop 0
	s_nop 0
	s_nop 0
	s_nop 0
	s_nop 0
	s_nop 0
	s_nop 0
	s_nop 0
	s_nop 0
	s_nop 0
	s_nop 0
	s_nop 0
	s_nop 0
	s_nop 0
	s_nop 0
	s_nop 0
	s_nop 0
	s_nop 0
	s_nop 0
	s_nop 0
	s_nop 0
	s_nop 0
	s_nop 0
	s_nop 0
	s_nop 0
	s_nop 0
	s_nop 0
	s_nop 0
	s_nop 0
	s_nop 0
	s_nop 0
	s_nop 0
	s_nop 0
	s_nop 0
	s_nop 0
	s_nop 0
	s_nop 0
	s_nop 0
	s_nop 0
	s_nop 0
	s_nop 0
	s_nop 0
	s_nop 0
	s_nop 0
	s_nop 0
	s_nop 0
	s_nop 0
	s_nop 0
	s_nop 0
	s_nop 0
	s_nop 0
	s_nop 0
	s_nop 0
	s_nop 0
	s_nop 0
	s_nop 0
	s_nop 0
	s_nop 0
	s_nop 0
	s_nop 0
	s_nop 0
	s_nop 0
	s_nop 0
	s_nop 0
	s_nop 0
	s_nop 0
	s_nop 0
	s_nop 0
	s_nop 0
	s_nop 0
	s_nop 0
	s_nop 0
	s_nop 0
	s_nop 0
	s_nop 0
	s_nop 0
	s_nop 0
	s_nop 0
	s_nop 0
	s_nop 0
	s_nop 0
	s_nop 0
	s_nop 0
	s_nop 0
	s_nop 0
	s_nop 0
	s_nop 0
	s_nop 0
	s_nop 0
	s_nop 0
	s_nop 0
	s_nop 0
	s_nop 0
	s_nop 0
	s_nop 0
	s_nop 0
	s_nop 0
	s_nop 0
	s_nop 0
	s_nop 0
	s_nop 0
	s_nop 0
	s_nop 0
	s_nop 0
	s_nop 0
	s_nop 0
	s_nop 0
	s_nop 0
	s_nop 0
	s_nop 0
	s_nop 0
	s_nop 0
	s_nop 0
	s_nop 0
	s_nop 0
	s_nop 0
	s_nop 0
	s_nop 0
	s_nop 0
	s_nop 0
	s_nop 0
	s_nop 0
	s_nop 0
	s_nop 0
	s_nop 0
	s_nop 0
	s_nop 0
	s_nop 0
	s_nop 0
	s_nop 0
	s_nop 0
	s_nop 0
.Lfbp_addr:
	v_alignbit_b32 v212, v191, v190, 2
	v_add_u32_e32 v214, v201, v212
	v_ashrrev_i32_e32 v215, 31, v214
	v_lshlrev_b64 v[236:237], 11, v[214:215]
	v_lshl_add_u64 v[236:237], s[6:7], 0, v[236:237]
	v_lshl_add_u64 v[236:237], v[236:237], 0, v[128:129]
	v_add_u32_e32 v214, v202, v212
	v_ashrrev_i32_e32 v215, 31, v214
	v_lshlrev_b64 v[238:239], 11, v[214:215]
	v_lshl_add_u64 v[238:239], s[6:7], 0, v[238:239]
	v_lshl_add_u64 v[238:239], v[238:239], 0, v[128:129]
	v_mbcnt_lo_u32_b32 v220, -1, 0
	v_mbcnt_hi_u32_b32 v220, -1, v220
	v_and_b32_e32 v220, 32, v220
	v_lshrrev_b32_e32 v220, 2, v220
	v_mov_b32_e32 v221, 0
	v_lshl_add_u64 v[236:237], v[236:237], 0, v[220:221]
	v_lshl_add_u64 v[238:239], v[238:239], 0, v[220:221]
	s_branch .Lfbp_addrd
.Lfa2_x:
	v_mbcnt_lo_u32_b32 v196, -1, 0
	v_mbcnt_hi_u32_b32 v196, -1, v196
	v_and_b32_e32 v196, 16, v196
	v_lshrrev_b32_e32 v197, 1, v196
	v_add_u32_e32 v196, v196, v197
	v_mov_b32_e32 v197, 0
	s_setprio 0
	v_mov_b32_e32 v107, v100
	s_barrier
	v_readlane_b32 s14, v252, 29
	v_mul_lo_u32 v112, v107, v102
	v_cvt_f32_i32_e32 v113, v112
	v_add_u32_e32 v115, v112, v107
	v_add_u32_e32 v124, v115, v107
	v_lshl_add_u32 v136, v107, 10, s1
	v_add_u32_e32 v107, v124, v107
	v_mul_f32_e32 v112, 0x3b490fdb, v113
	v_cvt_f32_i32_e32 v113, v115
	v_cvt_f32_i32_e32 v125, v124
	v_cvt_f32_i32_e32 v107, v107
	v_mul_f32_e32 v114, 0.15915494, v112
	v_mul_f32_e32 v113, 0x3b490fdb, v113
	v_mul_f32_e32 v125, 0x3b490fdb, v125
	v_mul_f32_e32 v107, 0x3b490fdb, v107
	v_mul_f32_e32 v115, 0.15915494, v113
	v_mul_f32_e32 v125, 0.15915494, v125
	v_mul_f32_e32 v107, 0.15915494, v107
	v_cos_f32_e32 v112, v114
	v_sin_f32_e32 v114, v114
	v_cos_f32_e32 v113, v115
	v_sin_f32_e32 v115, v115
	v_sin_f32_e32 v126, v125
	v_sin_f32_e32 v127, v107
	v_cos_f32_e32 v124, v125
	v_cos_f32_e32 v125, v107
	v_add_u32_e32 v107, s46, v136
	v_pk_mul_f32 v[130:131], v[148:149], v[114:115]
	v_pk_mul_f32 v[132:133], v[150:151], v[126:127]
	v_lshl_or_b32 v128, v107, 5, v102
	v_pk_fma_f32 v[130:131], v[220:221], v[112:113], v[130:131]
	v_pk_fma_f32 v[132:133], v[222:223], v[124:125], v[132:133]
	v_readlane_b32 s15, v252, 30
	v_cvt_pk_bf16_f32 v188, v130, v131
	v_cvt_pk_bf16_f32 v189, v132, v133
	s_branch .Lfa2_xd
